# v077 plus P3 post-pass items: per row the 8 split-K partial loads issued together (one round trip instead of eight) and the 64 hv broadcasts issued as eight batches of eight ds_bpermute with one wait
# speedup vs baseline: 1.0079x; 1.0079x over previous
; DI unsigned pk_bf16(float lo, float hi) { f32x2 v = {lo, hi}; bf16x2_t b = __builtin_convertvector(v, bf16x2_t); return __builtin_bit_cast(unsigned, b); }
; __device__ __forceinline__ float gelu_tanh_f(float x) {
;     const float y = 0.7978845608028654f * (x + 0.044715f * x * x * x);
;     const float e = __expf(2.f * y);
;     const float th = 1.f - 2.f / (1.f + e);
;     return 0.5f * x * (1.f + th);
; }
; __global__ void __launch_bounds__(512) fwd_kernel(Params P) {
;     ...
;                 for (int rr = 0; rr < 8; ++rr) { const int ridx = u * 64 + wid * 8 + rr; const int n = ridx & 1023, bgi = (ridx >> 10) & 3;
;                     float hs = cb;
; #pragma unroll
;                     for (int ks = 0; ks < 8; ++ks) hs += HIDP[((size_t)ks * 8192 + ridx) * 64 + lane];
;                     const float hv = pg8::gelu_tanh_f(hs); float o = 0.f;
; #pragma unroll
;                     for (int i2 = 0; i2 < 64; ++i2) o += __shfl(hv, i2) * wcol[i2];
;                     if (n == 1023) o = 0.f;
;                     const bf16_t ob = (bf16_t)(pk_bf16(o, 0.f) & 0xffffu);
;                     if (which == 0) KC[((size_t)bgi * 1024 + n) * 64 + lane] = ob; else VCT[((size_t)bgi * 64 + lane) * 1024 + n] = ob; }
.LBB0_628:
	v_lshl_add_u64 v[162:163], v[12:13], 0, s[24:25]
	s_add_i32 s3, s2, s24
	s_cmp_lg_u32 s3, 0
	v_add_co_u32_e32 v164, vcc, 0x18400000, v162
	s_nop 1
	v_addc_co_u32_e32 v165, vcc, 0, v163, vcc
	global_load_dword v228, v[164:165], off
	v_add_co_u32_e32 v164, vcc, 0x18600000, v162
	s_nop 1
	v_addc_co_u32_e32 v165, vcc, 0, v163, vcc
	global_load_dword v229, v[164:165], off
	v_add_co_u32_e32 v164, vcc, 0x18800000, v162
	s_nop 1
	v_addc_co_u32_e32 v165, vcc, 0, v163, vcc
	global_load_dword v230, v[164:165], off
	v_add_co_u32_e32 v164, vcc, 0x18a00000, v162
	s_nop 1
	v_addc_co_u32_e32 v165, vcc, 0, v163, vcc
	global_load_dword v231, v[164:165], off
	v_add_co_u32_e32 v164, vcc, 0x18c00000, v162
	s_nop 1
	v_addc_co_u32_e32 v165, vcc, 0, v163, vcc
	global_load_dword v232, v[164:165], off
	v_add_co_u32_e32 v164, vcc, 0x18e00000, v162
	s_nop 1
	v_addc_co_u32_e32 v165, vcc, 0, v163, vcc
	global_load_dword v233, v[164:165], off
	v_add_co_u32_e32 v164, vcc, 0x19000000, v162
	s_nop 1
	v_addc_co_u32_e32 v165, vcc, 0, v163, vcc
	global_load_dword v234, v[164:165], off
	v_add_co_u32_e32 v164, vcc, 0x19200000, v162
	s_nop 1
	v_addc_co_u32_e32 v165, vcc, 0, v163, vcc
	global_load_dword v235, v[164:165], off
	s_waitcnt vmcnt(0)
	v_add_f32_e32 v0, v68, v228
	v_add_f32_e32 v0, v0, v229
	v_add_f32_e32 v0, v0, v230
	v_add_f32_e32 v0, v0, v231
	v_add_f32_e32 v0, v0, v232
	v_add_f32_e32 v0, v0, v233
	v_add_f32_e32 v0, v0, v234
	v_add_f32_e32 v0, v0, v235
	v_mul_f32_e32 v162, 0x3d372713, v0
	v_mul_f32_e32 v162, v0, v162
	v_fma_f32 v162, v0, v162, v0
	v_mul_f32_e32 v162, 0x3f4c422a, v162
	v_add_f32_e32 v162, v162, v162
	v_mul_f32_e32 v162, 0x3fb8aa3b, v162
	v_exp_f32_e32 v162, v162
	v_mul_f32_e32 v0, 0.5, v0
	v_add_f32_e32 v162, 1.0, v162
	v_div_scale_f32 v163, s[26:27], v162, v162, 2.0
	v_rcp_f32_e32 v164, v163
	s_nop 0
	v_fma_f32 v165, -v163, v164, 1.0
	v_fmac_f32_e32 v164, v165, v164
	v_div_scale_f32 v165, vcc, 2.0, v162, 2.0
	v_mul_f32_e32 v166, v165, v164
	v_fma_f32 v167, -v163, v166, v165
	v_fmac_f32_e32 v166, v167, v164
	v_fma_f32 v163, -v163, v166, v165
	v_div_fmas_f32 v163, v163, v164, v166
	v_div_fixup_f32 v162, v163, v162, 2.0
	v_sub_f32_e32 v162, 1.0, v162
	v_add_f32_e32 v162, 1.0, v162
	v_mul_f32_e32 v0, v0, v162
	s_cselect_b64 vcc, -1, 0
	s_add_u32 s24, s24, 0x100
	s_addc_u32 s25, s25, 0
	s_cmpk_eq_i32 s24, 0x800
	ds_bpermute_b32 v236, v69, v0
	ds_bpermute_b32 v237, v70, v0
	ds_bpermute_b32 v238, v71, v0
	ds_bpermute_b32 v239, v72, v0
	ds_bpermute_b32 v240, v73, v0
	ds_bpermute_b32 v241, v74, v0
	ds_bpermute_b32 v242, v75, v0
	ds_bpermute_b32 v243, v76, v0
	s_waitcnt lgkmcnt(0)
	v_fma_f32 v164, v14, v236, 0
	v_fmac_f32_e32 v164, v15, v237
	v_fmac_f32_e32 v164, v16, v238
	v_fmac_f32_e32 v164, v17, v239
	v_fmac_f32_e32 v164, v18, v240
	v_fmac_f32_e32 v164, v19, v241
	v_fmac_f32_e32 v164, v20, v242
	v_fmac_f32_e32 v164, v21, v243
	ds_bpermute_b32 v236, v77, v0
	ds_bpermute_b32 v237, v78, v0
	ds_bpermute_b32 v238, v79, v0
	ds_bpermute_b32 v239, v80, v0
	ds_bpermute_b32 v240, v81, v0
	ds_bpermute_b32 v241, v82, v0
	ds_bpermute_b32 v242, v83, v0
	ds_bpermute_b32 v243, v84, v0
	s_waitcnt lgkmcnt(0)
	v_fmac_f32_e32 v164, v22, v236
	v_fmac_f32_e32 v164, v23, v237
	v_fmac_f32_e32 v164, v24, v238
	v_fmac_f32_e32 v164, v25, v239
	v_fmac_f32_e32 v164, v26, v240
	v_fmac_f32_e32 v164, v27, v241
	v_fmac_f32_e32 v164, v28, v242
	v_fmac_f32_e32 v164, v30, v243
	ds_bpermute_b32 v236, v85, v0
	ds_bpermute_b32 v237, v86, v0
	ds_bpermute_b32 v238, v87, v0
	ds_bpermute_b32 v239, v88, v0
	ds_bpermute_b32 v240, v89, v0
	ds_bpermute_b32 v241, v90, v0
	ds_bpermute_b32 v242, v91, v0
	ds_bpermute_b32 v243, v92, v0
	s_waitcnt lgkmcnt(0)
; DI unsigned pk_bf16(float lo, float hi) { f32x2 v = {lo, hi}; bf16x2_t b = __builtin_convertvector(v, bf16x2_t); return __builtin_bit_cast(unsigned, b); }
; __global__ void __launch_bounds__(512) fwd_kernel(Params P) {
;     ...
;                     for (int i2 = 0; i2 < 64; ++i2) o += __shfl(hv, i2) * wcol[i2];
;                     if (n == 1023) o = 0.f;
;                     const bf16_t ob = (bf16_t)(pk_bf16(o, 0.f) & 0xffffu);
;                     if (which == 0) KC[((size_t)bgi * 1024 + n) * 64 + lane] = ob; else VCT[((size_t)bgi * 64 + lane) * 1024 + n] = ob; }
;                 asm volatile("s_waitcnt vmcnt(0)" ::: "memory");
;                 __syncthreads();
;                 if (tid == 0) { __threadfence(); atomicAdd(CTL + CW_PPDONE + REPQ, 1u); }
	v_fmac_f32_e32 v164, v29, v236
	v_fmac_f32_e32 v164, v31, v237
	v_fmac_f32_e32 v164, v32, v238
	v_fmac_f32_e32 v164, v33, v239
	v_fmac_f32_e32 v164, v34, v240
	v_fmac_f32_e32 v164, v35, v241
	v_fmac_f32_e32 v164, v36, v242
	v_fmac_f32_e32 v164, v37, v243
	ds_bpermute_b32 v236, v93, v0
	ds_bpermute_b32 v237, v94, v0
	ds_bpermute_b32 v238, v95, v0
	ds_bpermute_b32 v239, v96, v0
	ds_bpermute_b32 v240, v97, v0
	ds_bpermute_b32 v241, v98, v0
	ds_bpermute_b32 v242, v99, v0
	ds_bpermute_b32 v243, v100, v0
	s_waitcnt lgkmcnt(0)
	v_fmac_f32_e32 v164, v38, v236
	v_fmac_f32_e32 v164, v39, v237
	v_fmac_f32_e32 v164, v40, v238
	v_fmac_f32_e32 v164, v41, v239
	v_fmac_f32_e32 v164, v42, v240
	v_fmac_f32_e32 v164, v43, v241
	v_fmac_f32_e32 v164, v44, v242
	v_fmac_f32_e32 v164, v45, v243
	ds_bpermute_b32 v236, v101, v0
	ds_bpermute_b32 v237, v102, v0
	ds_bpermute_b32 v238, v103, v0
	ds_bpermute_b32 v239, v104, v0
	ds_bpermute_b32 v240, v105, v0
	ds_bpermute_b32 v241, v106, v0
	ds_bpermute_b32 v242, v107, v0
	ds_bpermute_b32 v243, v108, v0
	s_waitcnt lgkmcnt(0)
	v_fmac_f32_e32 v164, v46, v236
	v_fmac_f32_e32 v164, v47, v237
	v_fmac_f32_e32 v164, v48, v238
	v_fmac_f32_e32 v164, v49, v239
	v_fmac_f32_e32 v164, v50, v240
	v_fmac_f32_e32 v164, v51, v241
	v_fmac_f32_e32 v164, v52, v242
	v_fmac_f32_e32 v164, v53, v243
	ds_bpermute_b32 v236, v109, v0
	ds_bpermute_b32 v237, v110, v0
	ds_bpermute_b32 v238, v111, v0
	ds_bpermute_b32 v239, v112, v0
	ds_bpermute_b32 v240, v113, v0
	ds_bpermute_b32 v241, v114, v0
	ds_bpermute_b32 v242, v115, v0
	ds_bpermute_b32 v243, v116, v0
	s_waitcnt lgkmcnt(0)
	v_fmac_f32_e32 v164, v54, v236
	v_fmac_f32_e32 v164, v55, v237
	v_fmac_f32_e32 v164, v56, v238
	v_fmac_f32_e32 v164, v57, v239
	v_fmac_f32_e32 v164, v58, v240
	v_fmac_f32_e32 v164, v59, v241
	v_fmac_f32_e32 v164, v60, v242
	v_fmac_f32_e32 v164, v61, v243
	ds_bpermute_b32 v236, v117, v0
	ds_bpermute_b32 v237, v118, v0
	ds_bpermute_b32 v238, v119, v0
	ds_bpermute_b32 v239, v120, v0
	ds_bpermute_b32 v240, v121, v0
	ds_bpermute_b32 v241, v149, v0
	ds_bpermute_b32 v242, v150, v0
	ds_bpermute_b32 v243, v151, v0
	s_waitcnt lgkmcnt(0)
	v_fmac_f32_e32 v164, v62, v236
	v_fmac_f32_e32 v164, v63, v237
	v_fmac_f32_e32 v164, v64, v238
	v_fmac_f32_e32 v164, v65, v239
	v_fmac_f32_e32 v164, v66, v240
	v_fmac_f32_e32 v164, v67, v241
	v_mul_f32_e32 v162, v2, v242
	v_mul_f32_e32 v163, v3, v243
	v_add_f32_e32 v162, v164, v162
	v_add_f32_e32 v164, v162, v163
	ds_bpermute_b32 v236, v152, v0
	ds_bpermute_b32 v237, v153, v0
	ds_bpermute_b32 v238, v154, v0
	ds_bpermute_b32 v239, v155, v0
	ds_bpermute_b32 v240, v156, v0
	ds_bpermute_b32 v241, v157, v0
	ds_bpermute_b32 v242, v158, v0
	ds_bpermute_b32 v243, v159, v0
	s_waitcnt lgkmcnt(0)
	v_mul_f32_e32 v162, v4, v236
	v_mul_f32_e32 v163, v5, v237
	v_add_f32_e32 v162, v164, v162
	v_add_f32_e32 v164, v162, v163
	v_mul_f32_e32 v162, v6, v238
	v_mul_f32_e32 v163, v7, v239
	v_add_f32_e32 v162, v164, v162
	v_add_f32_e32 v164, v162, v163
	v_mul_f32_e32 v162, v8, v240
	v_mul_f32_e32 v163, v9, v241
	v_add_f32_e32 v162, v164, v162
	v_add_f32_e32 v164, v162, v163
	v_mul_f32_e32 v162, v10, v242
	v_mul_f32_e32 v163, v11, v243
	v_add_f32_e32 v0, v164, v162
	v_add_f32_e32 v0, v0, v163
	v_cvt_pk_bf16_f32 v0, v0, s0
	v_cndmask_b32_e32 v164, 0, v0, vcc
	v_cndmask_b32_e64 v0, v161, v160, s[22:23]
	v_lshl_add_u64 v[162:163], v[0:1], 1, s[0:1]
	v_add_u32_e32 v160, 64, v160
	v_add_u32_e32 v161, 1, v161
	global_store_short v[162:163], v164, off
	s_cbranch_scc0 .LBB0_628
	s_waitcnt vmcnt(0)
	s_barrier
	s_mov_b64 s[0:1], exec
	v_readlane_b32 s2, v251, 20
	v_readlane_b32 s3, v251, 21
	s_and_b64 s[2:3], s[0:1], s[2:3]
	s_mov_b64 exec, s[2:3]
	s_cbranch_execz .LBB0_632
	s_mov_b64 s[2:3], exec
	v_mbcnt_lo_u32_b32 v0, s2, 0
	v_mbcnt_hi_u32_b32 v0, s3, v0
	v_cmp_eq_u32_e32 vcc, 0, v0
	s_and_b64 s[22:23], exec, vcc
	buffer_wbl2 sc1
	s_waitcnt vmcnt(0)
	buffer_inv sc1
	s_mov_b64 exec, s[22:23]
	s_cbranch_execz .LBB0_632
	s_bcnt1_i32_b64 s2, s[2:3]
	v_mov_b32_e32 v0, s2
	global_atomic_add v1, v0, s[34:35] offset:1280
